# P7 items 1 and 2: removed the full vmcnt drain behind the next-item prefetch (register park of im[1].x replaced by renamed address temps)
# speedup vs baseline: 1.0010x; 1.0010x over previous
.LBB0_1441:
	s_or_b64 exec, exec, s[68:69]
	v_mov_b32_e32 v62, 0
	v_mov_b32_e32 v63, 0
	v_mov_b32_e32 v64, 0
	v_mov_b32_e32 v65, 0
	s_and_saveexec_b64 s[68:69], s[10:11]
	s_cbranch_execz .LBB0_1443
	v_and_b32_e32 v62, 0xffffff80, v223
	v_ashrrev_i32_e32 v63, 31, v62
	v_lshl_add_u64 v[62:63], v[62:63], 1, v[90:91]
	global_load_dwordx4 v[62:65], v[62:63], off nt
.LBB0_1443:
	s_or_b64 exec, exec, s[68:69]
	v_mov_b32_e32 v78, 0
	v_mov_b32_e32 v82, 0
	v_mov_b32_e32 v83, 0
	v_mov_b32_e32 v84, 0
	v_mov_b32_e32 v85, 0
	s_and_saveexec_b64 s[68:69], s[12:13]
	s_cbranch_execz .LBB0_1445
	v_and_b32_e32 v80, 0xffffff80, v196
	v_add_u32_e32 v80, 0x2000, v80
	v_ashrrev_i32_e32 v81, 31, v80
	v_lshl_add_u64 v[80:81], v[80:81], 1, v[90:91]
	global_load_dwordx4 v[82:85], v[80:81], off nt
.LBB0_1445:
	s_or_b64 exec, exec, s[68:69]
	v_mov_b32_e32 v79, 0
	v_mov_b32_e32 v80, 0
	v_mov_b32_e32 v81, 0
	s_and_saveexec_b64 s[68:69], s[14:15]
	s_cbranch_execz .LBB0_1447
	v_and_b32_e32 v78, 0xffffff80, v196
	v_add_u32_e32 v78, 0x3000, v78
	v_ashrrev_i32_e32 v79, 31, v78
	v_lshl_add_u64 v[78:79], v[78:79], 1, v[90:91]
	global_load_dwordx4 v[78:81], v[78:79], off nt
.LBB0_1447:
	s_or_b64 exec, exec, s[68:69]
	v_mov_b32_e32 v224, 0
	v_mov_b32_e32 v86, 0
	v_mov_b32_e32 v87, 0
	v_mov_b32_e32 v88, 0
	v_mov_b32_e32 v89, 0
	s_and_saveexec_b64 s[68:69], s[16:17]
	s_cbranch_execz .LBB0_1449
	v_and_b32_e32 v86, 0xffffff80, v196
	v_add_u32_e32 v86, 0x4000, v86
	v_ashrrev_i32_e32 v87, 31, v86
	v_lshl_add_u64 v[86:87], v[86:87], 1, v[90:91]
	global_load_dwordx4 v[86:89], v[86:87], off nt
.LBB0_1449:
	s_or_b64 exec, exec, s[68:69]
	v_mov_b32_e32 v227, 0
	v_mov_b32_e32 v226, 0
	v_mov_b32_e32 v225, 0
	s_and_saveexec_b64 s[68:69], s[18:19]
	s_cbranch_execz .LBB0_1451
	s_and_b32 s26, s60, 0x3ffffff
	s_lshl_b32 s25, s25, 6
	s_lshl_b64 s[26:27], s[26:27], 16
	s_add_u32 s26, s34, s26
	s_addc_u32 s27, s35, s27
	s_lshl_b32 s25, s25, 2
	s_add_u32 s26, s26, s25
	s_mov_b32 s65, 0
	s_addc_u32 s27, s27, 0
	v_ashrrev_i32_e32 v173, 31, v172
	v_lshl_add_u64 v[90:91], v[172:173], 2, s[26:27]
	s_lshl_b64 s[26:27], s[64:65], 2
	s_add_u32 s26, s34, s26
	v_add_co_u32_e32 v92, vcc, 0xf000000, v90
	s_addc_u32 s27, s35, s27
	s_lshl_b32 s50, s64, 1
	s_mov_b32 s51, s65
	v_addc_co_u32_e32 v93, vcc, 0, v91, vcc
	s_lshl_b64 s[50:51], s[50:51], 2
	v_add_co_u32_e32 v90, vcc, 0xf008000, v90
	s_add_u32 s50, s34, s50
	s_nop 0
	v_addc_co_u32_e32 v91, vcc, 0, v91, vcc
	v_mov_b32_e32 v225, 0xf210000
	s_addc_u32 s51, s35, s51
	v_mov_b32_e32 v94, 0xf200000
	global_load_dword v224, v[92:93], off
	global_load_dword v226, v[90:91], off
	global_load_dword v225, v225, s[26:27]
	global_load_dword v227, v94, s[50:51]
.LBB0_1451:
	s_or_b64 exec, exec, s[68:69]
.LBB0_1452:
	s_lshl_b32 s24, s24, 6
	s_and_b32 s24, s24, 0xf40
	v_or_b32_e32 v90, s24, v199
	v_or_b32_e32 v90, s72, v90
	v_or_b32_e32 v192, s40, v90
	v_mov_b32_e32 v193, s41
	v_lshlrev_b64 v[90:91], 10, v[192:193]
	v_lshl_add_u64 v[90:91], s[42:43], 0, v[90:91]
	s_mov_b32 s37, 0
	v_lshl_add_u64 v[90:91], v[90:91], 0, s[36:37]
	v_lshl_add_u64 v[90:91], v[168:169], 1, v[90:91]
	global_load_dwordx4 v[102:105], v[176:177], off offset:16
	global_load_dwordx4 v[110:113], v[176:177], off
	global_load_dwordx4 v[106:109], v[90:91], off
	global_load_dwordx4 v[94:97], v[90:91], off offset:64
	s_nop 0
	global_load_dwordx4 v[90:93], v[176:177], off offset:144
	global_load_dwordx4 v[98:101], v[176:177], off offset:128
	ds_read_b64_tr_b16 v[114:115], v201 offset:17408
	ds_read_b64_tr_b16 v[116:117], v201 offset:17984
	ds_read_b128 v[126:129], v210
	ds_read_b64_tr_b16 v[130:131], v201 offset:22016
	ds_read_b64_tr_b16 v[132:133], v201 offset:22592
	ds_read_b128 v[122:125], v210 offset:64
	s_waitcnt lgkmcnt(3)
	v_mfma_f32_16x16x32_bf16 v[134:137], v[114:117], v[126:129], 0
	ds_read_b64_tr_b16 v[138:139], v201 offset:26624
	ds_read_b64_tr_b16 v[140:141], v201 offset:27200
	ds_read_b128 v[118:121], v210 offset:128
	ds_read_b128 v[114:117], v210 offset:192
	ds_read_b64_tr_b16 v[142:143], v201 offset:31232
	ds_read_b64_tr_b16 v[144:145], v201 offset:31808
	ds_read_b32 v173, v213
	ds_read2st64_b32 v[194:195], v214 offset0:2 offset1:3
	s_andn2_b64 vcc, exec, s[28:29]
	s_waitcnt lgkmcnt(8)
	v_mfma_f32_16x16x32_bf16 v[130:133], v[130:133], v[122:125], v[134:137]
	s_waitcnt lgkmcnt(5)
	v_mfma_f32_16x16x32_bf16 v[130:133], v[138:141], v[118:121], v[130:133]
	s_nop 0
	v_cndmask_b32_e64 v134, 0, 1, s[28:29]
	v_mov_b32_e32 v136, 0
	v_cmp_ne_u32_e64 s[24:25], 1, v134
	s_waitcnt lgkmcnt(2)
	v_mfma_f32_16x16x32_bf16 v[130:133], v[142:145], v[114:117], v[130:133]
	s_cbranch_vccnz .LBB0_1454
	v_mov_b32_e32 v134, s37
	v_cmp_gt_u32_e32 vcc, v200, v199
	s_nop 4
	v_cndmask_b32_e32 v134, v130, v134, vcc
	v_cmp_lt_u32_e32 vcc, v200, v199
	s_nop 1
	v_cndmask_b32_e32 v130, v134, v130, vcc
	v_cndmask_b32_e32 v131, 0, v131, vcc
	v_cmp_le_u32_e32 vcc, v203, v199
	s_nop 1
	v_cndmask_b32_e32 v132, 0, v132, vcc
	v_cmp_le_u32_e32 vcc, v202, v199
	s_nop 1
	v_cndmask_b32_e32 v133, 0, v133, vcc

.LBB0_1488:
	s_or_b64 exec, exec, s[66:67]
	v_mov_b32_e32 v18, 0
	v_mov_b32_e32 v19, 0
	v_mov_b32_e32 v20, 0
	v_mov_b32_e32 v21, 0
	s_and_saveexec_b64 s[66:67], s[10:11]
	s_cbranch_execz .LBB0_1490
	v_and_b32_e32 v18, 0xffffff80, v223
	v_ashrrev_i32_e32 v19, 31, v18
	v_lshl_add_u64 v[18:19], v[18:19], 1, v[46:47]
	global_load_dwordx4 v[18:21], v[18:19], off nt
.LBB0_1490:
	s_or_b64 exec, exec, s[66:67]
	v_mov_b32_e32 v34, 0
	v_mov_b32_e32 v38, 0
	v_mov_b32_e32 v39, 0
	v_mov_b32_e32 v40, 0
	v_mov_b32_e32 v41, 0
	s_and_saveexec_b64 s[66:67], s[12:13]
	s_cbranch_execz .LBB0_1492
	v_and_b32_e32 v36, 0xffffff80, v196
	v_add_u32_e32 v36, 0x2000, v36
	v_ashrrev_i32_e32 v37, 31, v36
	v_lshl_add_u64 v[36:37], v[36:37], 1, v[46:47]
	global_load_dwordx4 v[38:41], v[36:37], off nt
.LBB0_1492:
	s_or_b64 exec, exec, s[66:67]
	v_mov_b32_e32 v35, 0
	v_mov_b32_e32 v36, 0
	v_mov_b32_e32 v37, 0
	s_and_saveexec_b64 s[66:67], s[14:15]
	s_cbranch_execz .LBB0_1494
	v_and_b32_e32 v34, 0xffffff80, v196
	v_add_u32_e32 v34, 0x3000, v34
	v_ashrrev_i32_e32 v35, 31, v34
	v_lshl_add_u64 v[34:35], v[34:35], 1, v[46:47]
	global_load_dwordx4 v[34:37], v[34:35], off nt
.LBB0_1494:
	s_or_b64 exec, exec, s[66:67]
	v_mov_b32_e32 v219, 0
	v_mov_b32_e32 v42, 0
	v_mov_b32_e32 v43, 0
	v_mov_b32_e32 v44, 0
	v_mov_b32_e32 v45, 0
	s_and_saveexec_b64 s[66:67], s[16:17]
	s_cbranch_execz .LBB0_1496
	v_and_b32_e32 v42, 0xffffff80, v196
	v_add_u32_e32 v42, 0x4000, v42
	v_ashrrev_i32_e32 v43, 31, v42
	v_lshl_add_u64 v[42:43], v[42:43], 1, v[46:47]
	global_load_dwordx4 v[42:45], v[42:43], off nt
.LBB0_1496:
	s_or_b64 exec, exec, s[66:67]
	v_mov_b32_e32 v220, 0
	v_mov_b32_e32 v222, 0
	v_mov_b32_e32 v221, 0
	s_and_saveexec_b64 s[66:67], s[18:19]
	s_cbranch_execz .LBB0_1498
	s_and_b32 s30, s60, 0x3ffffff
	s_lshl_b32 s37, s37, 6
	s_lshl_b64 s[30:31], s[30:31], 16
	s_add_u32 s30, s34, s30
	s_addc_u32 s31, s35, s31
	s_lshl_b32 s37, s37, 2
	s_add_u32 s30, s30, s37
	s_mov_b32 s63, 0
	s_addc_u32 s31, s31, 0
	v_ashrrev_i32_e32 v173, 31, v172
	v_lshl_add_u64 v[46:47], v[172:173], 2, s[30:31]
	s_lshl_b64 s[30:31], s[62:63], 2
	s_add_u32 s30, s34, s30
	v_add_co_u32_e32 v48, vcc, 0xf000000, v46
	s_addc_u32 s31, s35, s31
	s_lshl_b32 s50, s62, 1
	s_mov_b32 s51, s63
	v_addc_co_u32_e32 v49, vcc, 0, v47, vcc
	s_lshl_b64 s[50:51], s[50:51], 2
	v_add_co_u32_e32 v46, vcc, 0xf008000, v46
	s_add_u32 s50, s34, s50
	s_nop 0
	v_addc_co_u32_e32 v47, vcc, 0, v47, vcc
	v_mov_b32_e32 v221, 0xf210000
	s_addc_u32 s51, s35, s51
	v_mov_b32_e32 v50, 0xf200000
	global_load_dword v219, v[48:49], off
	global_load_dword v222, v[46:47], off
	global_load_dword v221, v221, s[30:31]
	global_load_dword v220, v50, s[50:51]
.LBB0_1498:
	s_or_b64 exec, exec, s[66:67]
.LBB0_1499:
	s_lshl_b32 s30, s64, 6
	s_and_b32 s30, s30, 0xf80
	v_or_b32_e32 v46, s30, v199
	v_or_b32_e32 v46, s72, v46
	v_or_b32_e32 v122, s40, v46
	v_mov_b32_e32 v123, s41
	v_lshlrev_b64 v[46:47], 10, v[122:123]
	v_lshl_add_u64 v[46:47], s[42:43], 0, v[46:47]
	s_mov_b32 s37, 0
	v_lshl_add_u64 v[46:47], v[46:47], 0, s[36:37]
	v_lshl_add_u64 v[50:51], v[168:169], 1, v[46:47]
	ds_read_b64_tr_b16 v[46:47], v201 offset:17408
	ds_read_b64_tr_b16 v[48:49], v201 offset:17984
	global_load_dwordx4 v[58:61], v[176:177], off offset:16
	global_load_dwordx4 v[66:69], v[176:177], off
	ds_read_b128 v[82:85], v210
	global_load_dwordx4 v[62:65], v[50:51], off
	s_nop 0
	global_load_dwordx4 v[50:53], v[50:51], off offset:64
	ds_read_b128 v[74:77], v210 offset:64
	ds_read_b64_tr_b16 v[70:71], v201 offset:22016
	ds_read_b64_tr_b16 v[72:73], v201 offset:22592
	s_waitcnt lgkmcnt(3)
	v_mfma_f32_16x16x32_bf16 v[78:81], v[46:49], v[82:85], 0
	global_load_dwordx4 v[46:49], v[176:177], off offset:144
	global_load_dwordx4 v[54:57], v[176:177], off offset:128
	ds_read_b64_tr_b16 v[86:87], v201 offset:26624
	ds_read_b64_tr_b16 v[88:89], v201 offset:27200
	s_and_b64 vcc, exec, s[24:25]
	s_waitcnt lgkmcnt(2)
	v_mfma_f32_16x16x32_bf16 v[90:93], v[70:73], v[74:77], v[78:81]
	ds_read_b64_tr_b16 v[94:95], v201 offset:31232
	ds_read_b64_tr_b16 v[96:97], v201 offset:31808
	s_nop 0
	ds_read_b128 v[78:81], v210 offset:128
	ds_read_b128 v[70:73], v210 offset:192
	ds_read_b32 v126, v213
	ds_read2st64_b32 v[124:125], v214 offset0:2 offset1:3
	s_waitcnt lgkmcnt(3)
	v_mfma_f32_16x16x32_bf16 v[86:89], v[86:89], v[78:81], v[90:93]
	s_waitcnt lgkmcnt(2)
	v_mfma_f32_16x16x32_bf16 v[86:89], v[94:97], v[70:73], v[86:89]
	s_nop 0
	v_mov_b32_e32 v92, 0
	s_cbranch_vccnz .LBB0_1501
	v_mov_b32_e32 v90, s37
	v_cmp_gt_u32_e32 vcc, v200, v199
	s_nop 2
	v_cndmask_b32_e32 v90, v86, v90, vcc
	v_cmp_lt_u32_e32 vcc, v200, v199
	s_nop 1
	v_cndmask_b32_e32 v86, v90, v86, vcc
	v_cndmask_b32_e32 v87, 0, v87, vcc
	v_cmp_le_u32_e32 vcc, v203, v199
	s_nop 1
	v_cndmask_b32_e32 v88, 0, v88, vcc
	v_cmp_le_u32_e32 vcc, v202, v199
	s_nop 1
	v_cndmask_b32_e32 v89, 0, v89, vcc
